# mixer work queue: next ticket (atomicAdd) prefetched while the current unit runs
# speedup vs baseline: 1.0022x; 1.0022x over previous
; #define LAS __attribute__((address_space(3)))
; __device__ __forceinline__ void phase_mixer(CArgs& a, int l, unsigned char* lds_g, LAS unsigned char* lds, int dup) {
;     int tid = threadIdx.x; asm volatile("" : "+v"(tid));
;     unsigned* ctr = (unsigned*)(a.ws + WS_CTL) + CW_QUEUE + 64 * l + 32 * dup;
;     volatile LAS unsigned* qw = (volatile LAS unsigned*)(lds + LDS_QWORD);
;     const bf16_t* PROJ = (const bf16_t*)(a.ws + WS_PROJ); const bf16_t* QB = (const bf16_t*)(a.ws + WS_QB); const bf16_t* KB = (const bf16_t*)(a.ws + WS_KB);
;     const bf16_t* KVB = (const bf16_t*)(a.ws + WS_KVB); bf16_t* Z = (bf16_t*)(a.ws + WS_HZ);
;     const int nG = (l == 0) ? NCHUNK * 4 : 256 * 4, nC = (l == 0) ? 48 : 0, total = 768 + nG + nC;
;     for (;;) {
;         __syncthreads();
;         if (tid == 0) *qw = atomicAdd(ctr, 1u);
.LBB0_29:
	s_mul_i32 s5, s34, 0x5c00000
	s_mul_hi_i32 s4, s34, 0x5c00000
	s_add_u32 s5, s56, s5
	s_addc_u32 s4, s57, s4
	s_add_u32 s36, s5, 0x100000
	s_addc_u32 s37, s4, 0
	v_ashrrev_i32_e32 v228, 6, v227
	v_readlane_b32 s4, v255, 33
	v_and_b32_e32 v200, 63, v227
	s_cmp_lt_i32 s6, 3
	v_add_u32_e32 v202, s4, v228
	v_writelane_b32 v255, s6, 52
	s_cbranch_scc1 .LBB0_34
	s_mov_b64 s[48:49], 0
	s_mov_b64 s[12:13], -1
	s_cmp_gt_i32 s6, 3
	s_mov_b64 s[62:63], 0
	s_cbranch_scc0 .LBB0_35
	v_readlane_b32 s4, v255, 52
	s_cmp_gt_i32 s4, 4
	s_cbranch_scc0 .LBB0_163
	s_cmp_eq_u32 s4, 5
	s_mov_b64 s[62:63], -1
	s_cbranch_scc0 .LBB0_164
	s_lshl_b32 s4, s34, 6
	s_ashr_i32 s5, s4, 31
	s_lshl_b64 s[4:5], s[4:5], 2
	s_add_u32 s44, s56, s4
	s_addc_u32 s45, s57, s5
	s_add_u32 s50, s56, 0x18500000
	s_addc_u32 s51, s57, 0
	s_add_u32 s58, s56, 0x20d00000
	s_addc_u32 s59, s57, 0
	s_add_u32 s66, s56, 0x24900000
	s_addc_u32 s67, s57, 0
	s_add_u32 s68, s56, 0xb900000
	v_readlane_b32 s4, v255, 46
	s_addc_u32 s69, s57, 0
	s_add_i32 s4, s4, 8
	s_cmp_gt_u32 s4, 18
	s_cselect_b64 s[70:71], -1, 0
	s_cmp_lt_u32 s4, 19
	s_movk_i32 s4, 0x740
	s_cselect_b32 s75, s4, 0x700
	s_movk_i32 s4, 0x770
	v_mov_b32_e32 v0, v201
	v_readlane_b32 s5, v255, 47
	s_cselect_b32 s12, s4, 0x700
	s_movk_i32 s4, 0xf8c0
	s_cselect_b32 s91, s4, 0xfffff900
	s_load_dwordx2 s[4:5], s[0:1], 0xb8
	v_readlane_b32 s6, v255, 48
	s_add_u32 s13, s56, 0x26300000
	v_readlane_b32 s7, v255, 49
	s_addc_u32 s72, s57, 0
	s_lshl_b32 s6, s34, 7
	s_ashr_i32 s7, s6, 31
	s_lshl_b64 s[6:7], s[6:7], 2
	s_waitcnt lgkmcnt(0)
	s_add_u32 s52, s4, s6
	v_cmp_eq_u32_e64 s[38:39], 0, v0
	s_addc_u32 s53, s5, s7
	s_nop 3
	s_and_saveexec_b64 s[14:15], s[38:39]
	s_cbranch_execz .Lq_pre_done
	v_mov_b32_e32 v200, 1
	s_nop 0
	global_atomic_add v200, v1, v200, s[44:45] offset:256 sc0
.Lq_pre_done:
	s_or_b64 exec, exec, s[14:15]
	s_branch .LBB0_72

; __device__ __forceinline__ void phase_mixer(CArgs& a, int l, unsigned char* lds_g, LAS unsigned char* lds, int dup) {
;     ...
;     for (;;) {
;         __syncthreads();
;         if (tid == 0) *qw = atomicAdd(ctr, 1u);
;         __syncthreads();
;         const int idx = (int)*qw;
;         if (idx >= total) break;
.LBB0_72:
	s_barrier
	s_and_saveexec_b64 s[8:9], s[38:39]
	s_cbranch_execz .LBB0_76
	s_waitcnt vmcnt(0)
	v_readfirstlane_b32 s4, v200
	s_nop 1
	v_mov_b32_e32 v0, s4
	v_readlane_b32 s4, v255, 35
	s_nop 1
	v_mov_b32_e32 v2, s4
	ds_write_b32 v2, v0
	v_mov_b32_e32 v200, 1
	s_nop 0
	global_atomic_add v200, v1, v200, s[44:45] offset:256 sc0
